# hand-written conformer conv block unit: vectorised GLU loads, register sliding window for the depthwise conv, interleaved LayerNorm reductions
# speedup vs baseline: 1.0803x; 1.0361x over previous
.LBB0_347:
	s_cmp_ge_i32 s13, s10
	s_mov_b64 s[0:1], -1
	s_cbranch_scc0 .LBB0_369
	s_cmp_ge_i32 s13, s11
	s_cbranch_scc0 .LBB0_364
	s_sub_i32 s0, s13, s11
	s_lshl_b32 s6, s0, 5
	s_cmp_gt_i32 s0, 0x1ff
	s_cbranch_scc1 .Lcv_ctx
	s_and_b32 s70, s6, 0xfe0
	s_and_b32 s71, s6, 0xfffff000
	s_or_b32 s71, s71, 0x400
	s_movk_i32 s72, 0x1000
	s_branch .Lcv_dec
.Lcv_ctx:
	s_and_b32 s70, s6, 0xe0
	s_and_b32 s71, s6, 0x7fffff00
	s_add_i32 s71, s71, 0xffffc000
	s_movk_i32 s72, 0x100
.Lcv_dec:
	v_and_b32_e32 v104, 0xff, v143
	v_lshlrev_b32_e32 v105, 2, v104
	v_lshrrev_b32_e32 v106, 8, v143
	v_lshrrev_b32_e32 v107, 5, v143
	v_and_b32_e32 v108, 31, v143
	v_lshlrev_b32_e32 v110, 5, v108
	v_lshl_add_u32 v110, v107, 10, v110
	v_lshlrev_b32_e32 v108, 4, v108
	v_mul_u32_u24_e32 v109, 0xe00, v107
	v_add_u32_e32 v109, v109, v108
	s_add_i32 s0, s71, s70
	s_sub_i32 s0, s0, 15
	s_mul_i32 s0, s0, 0xe00
	s_ashr_i32 s1, s0, 31
	v_readlane_b32 s6, v247, 26
	v_readlane_b32 s7, v247, 27
	s_add_u32 s6, s6, s0
	s_addc_u32 s7, s7, s1
	s_sub_i32 s73, s70, 15
	v_mov_b32_e32 v32, 0
	v_mov_b32_e32 v33, 0
	v_mov_b32_e32 v34, 0
	v_mov_b32_e32 v35, 0
	v_mov_b32_e32 v36, 0
	v_mov_b32_e32 v37, 0
	v_mov_b32_e32 v38, 0
	v_mov_b32_e32 v39, 0
	v_mov_b32_e32 v40, 0
	v_mov_b32_e32 v41, 0
	v_mov_b32_e32 v42, 0
	v_mov_b32_e32 v43, 0
	v_mov_b32_e32 v44, 0
	v_mov_b32_e32 v45, 0
	v_mov_b32_e32 v46, 0
	v_mov_b32_e32 v47, 0
	v_mov_b32_e32 v48, 0
	v_mov_b32_e32 v49, 0
	v_mov_b32_e32 v50, 0
	v_mov_b32_e32 v51, 0
	v_mov_b32_e32 v52, 0
	v_mov_b32_e32 v53, 0
	v_mov_b32_e32 v54, 0
	v_mov_b32_e32 v55, 0
	v_mov_b32_e32 v56, 0
	v_mov_b32_e32 v57, 0
	v_mov_b32_e32 v58, 0
	v_mov_b32_e32 v59, 0
	v_mov_b32_e32 v60, 0
	v_mov_b32_e32 v61, 0
	v_mov_b32_e32 v62, 0
	v_mov_b32_e32 v63, 0
	v_add_u32_e32 v112, 0, v107
	v_add_u32_e32 v113, s73, v112
	v_cmp_gt_u32_e64 s[8:9], s72, v113
	v_cmp_gt_u32_e64 s[0:1], 62, v112
	s_and_b64 s[8:9], s[8:9], s[0:1]
	s_and_saveexec_b64 s[0:1], s[8:9]
	s_cbranch_execz .Lcv_skip0
	global_load_dwordx4 v[32:35], v109, s[6:7]
	global_load_dwordx4 v[36:39], v109, s[6:7] offset:512
.Lcv_skip0:
	s_mov_b64 exec, s[0:1]
	s_add_u32 s6, s6, 0xe000
	s_addc_u32 s7, s7, 0
	v_add_u32_e32 v112, 16, v107
	v_add_u32_e32 v113, s73, v112
	v_cmp_gt_u32_e64 s[8:9], s72, v113
	v_cmp_gt_u32_e64 s[0:1], 62, v112
	s_and_b64 s[8:9], s[8:9], s[0:1]
	s_and_saveexec_b64 s[0:1], s[8:9]
	s_cbranch_execz .Lcv_skip1
	global_load_dwordx4 v[40:43], v109, s[6:7]
	global_load_dwordx4 v[44:47], v109, s[6:7] offset:512
.Lcv_skip1:
	s_mov_b64 exec, s[0:1]
	s_add_u32 s6, s6, 0xe000
	s_addc_u32 s7, s7, 0
	v_add_u32_e32 v112, 32, v107
	v_add_u32_e32 v113, s73, v112
	v_cmp_gt_u32_e64 s[8:9], s72, v113
	v_cmp_gt_u32_e64 s[0:1], 62, v112
	s_and_b64 s[8:9], s[8:9], s[0:1]
	s_and_saveexec_b64 s[0:1], s[8:9]
	s_cbranch_execz .Lcv_skip2
	global_load_dwordx4 v[48:51], v109, s[6:7]
	global_load_dwordx4 v[52:55], v109, s[6:7] offset:512
.Lcv_skip2:
	s_mov_b64 exec, s[0:1]
	s_add_u32 s6, s6, 0xe000
	s_addc_u32 s7, s7, 0
	v_add_u32_e32 v112, 48, v107
	v_add_u32_e32 v113, s73, v112
	v_cmp_gt_u32_e64 s[8:9], s72, v113
	v_cmp_gt_u32_e64 s[0:1], 62, v112
	s_and_b64 s[8:9], s[8:9], s[0:1]
	s_and_saveexec_b64 s[0:1], s[8:9]
	s_cbranch_execz .Lcv_skip3
	global_load_dwordx4 v[56:59], v109, s[6:7]
	global_load_dwordx4 v[60:63], v109, s[6:7] offset:512
.Lcv_skip3:
	s_mov_b64 exec, s[0:1]
	s_lshl_b32 s0, s14, 2
	s_add_u32 s2, s20, s0
	s_addc_u32 s3, s21, 0
	global_load_dword v0, v105, s[2:3] offset:0
	global_load_dword v1, v105, s[2:3] offset:1024
	global_load_dword v2, v105, s[2:3] offset:2048
	global_load_dword v3, v105, s[2:3] offset:3072
	s_add_u32 s2, s2, 0x1000
	s_addc_u32 s3, s3, 0
	global_load_dword v4, v105, s[2:3] offset:0
	global_load_dword v5, v105, s[2:3] offset:1024
	global_load_dword v6, v105, s[2:3] offset:2048
	global_load_dword v7, v105, s[2:3] offset:3072
	s_add_u32 s2, s2, 0x1000
	s_addc_u32 s3, s3, 0
	global_load_dword v8, v105, s[2:3] offset:0
	global_load_dword v9, v105, s[2:3] offset:1024
	global_load_dword v10, v105, s[2:3] offset:2048
	global_load_dword v11, v105, s[2:3] offset:3072
	s_add_u32 s2, s2, 0x1000
	s_addc_u32 s3, s3, 0
	global_load_dword v12, v105, s[2:3] offset:0
	global_load_dword v13, v105, s[2:3] offset:1024
	global_load_dword v14, v105, s[2:3] offset:2048
	global_load_dword v15, v105, s[2:3] offset:3072
	s_add_u32 s2, s2, 0x1000
	s_addc_u32 s3, s3, 0
	global_load_dword v16, v105, s[2:3] offset:0
	global_load_dword v17, v105, s[2:3] offset:1024
	global_load_dword v18, v105, s[2:3] offset:2048
	global_load_dword v19, v105, s[2:3] offset:3072
	s_add_u32 s2, s2, 0x1000
	s_addc_u32 s3, s3, 0
	global_load_dword v20, v105, s[2:3] offset:0
	global_load_dword v21, v105, s[2:3] offset:1024
	global_load_dword v22, v105, s[2:3] offset:2048
	global_load_dword v23, v105, s[2:3] offset:3072
	s_add_u32 s2, s2, 0x1000
	s_addc_u32 s3, s3, 0
	global_load_dword v24, v105, s[2:3] offset:0
	global_load_dword v25, v105, s[2:3] offset:1024
	global_load_dword v26, v105, s[2:3] offset:2048
	global_load_dword v27, v105, s[2:3] offset:3072
	s_add_u32 s2, s2, 0x1000
	s_addc_u32 s3, s3, 0
	global_load_dword v28, v105, s[2:3] offset:0
	global_load_dword v29, v105, s[2:3] offset:1024
	global_load_dword v30, v105, s[2:3] offset:2048
	v_readlane_b32 s0, v244, 21
	s_lshl_b32 s0, s0, 2
	s_add_u32 s2, s22, s0
	s_addc_u32 s3, s23, 0
	global_load_dword v31, v105, s[2:3]
	v_and_b32_e32 v111, 63, v143
	v_lshlrev_b32_e32 v111, 4, v111
	global_load_dwordx4 v[96:99], v111, s[36:37]
	global_load_dwordx4 v[100:103], v111, s[38:39]
	s_waitcnt vmcnt(0)
	v_lshlrev_b32_e32 v64, 16, v32
	v_and_b32_e32 v65, 0xffff0000, v32
	v_lshlrev_b32_e32 v128, 16, v36
	v_and_b32_e32 v129, 0xffff0000, v36
	v_lshlrev_b32_e32 v66, 16, v33
	v_and_b32_e32 v67, 0xffff0000, v33
	v_lshlrev_b32_e32 v130, 16, v37
	v_and_b32_e32 v131, 0xffff0000, v37
	v_lshlrev_b32_e32 v68, 16, v34
	v_and_b32_e32 v69, 0xffff0000, v34
	v_lshlrev_b32_e32 v132, 16, v38
	v_and_b32_e32 v133, 0xffff0000, v38
	v_lshlrev_b32_e32 v70, 16, v35
	v_and_b32_e32 v71, 0xffff0000, v35
	v_lshlrev_b32_e32 v134, 16, v39
	v_and_b32_e32 v135, 0xffff0000, v39
	v_mul_f32_e32 v112, 0xbfb8aa3b, v128
	v_mul_f32_e32 v113, 0xbfb8aa3b, v129
	v_mul_f32_e32 v114, 0xbfb8aa3b, v130
	v_mul_f32_e32 v115, 0xbfb8aa3b, v131
	v_mul_f32_e32 v116, 0xbfb8aa3b, v132
	v_mul_f32_e32 v117, 0xbfb8aa3b, v133
	v_mul_f32_e32 v118, 0xbfb8aa3b, v134
	v_mul_f32_e32 v119, 0xbfb8aa3b, v135
	v_exp_f32_e32 v112, v112
	v_exp_f32_e32 v113, v113
	v_exp_f32_e32 v114, v114
	v_exp_f32_e32 v115, v115
	v_exp_f32_e32 v116, v116
	v_exp_f32_e32 v117, v117
	v_exp_f32_e32 v118, v118
	v_exp_f32_e32 v119, v119
	s_nop 0
	v_add_f32_e32 v112, 1.0, v112
	v_add_f32_e32 v113, 1.0, v113
	v_add_f32_e32 v114, 1.0, v114
	v_add_f32_e32 v115, 1.0, v115
	v_add_f32_e32 v116, 1.0, v116
	v_add_f32_e32 v117, 1.0, v117
	v_add_f32_e32 v118, 1.0, v118
	v_add_f32_e32 v119, 1.0, v119
	v_rcp_f32_e32 v120, v112
	v_rcp_f32_e32 v121, v113
	v_rcp_f32_e32 v122, v114
	v_rcp_f32_e32 v123, v115
	v_rcp_f32_e32 v124, v116
	v_rcp_f32_e32 v125, v117
	v_rcp_f32_e32 v126, v118
	v_rcp_f32_e32 v127, v119
	s_nop 0
	v_fma_f32 v112, -v112, v120, 1.0
	v_fma_f32 v113, -v113, v121, 1.0
	v_fma_f32 v114, -v114, v122, 1.0
	v_fma_f32 v115, -v115, v123, 1.0
	v_fma_f32 v116, -v116, v124, 1.0
	v_fma_f32 v117, -v117, v125, 1.0
	v_fma_f32 v118, -v118, v126, 1.0
	v_fma_f32 v119, -v119, v127, 1.0
	v_fma_f32 v120, v112, v120, v120
	v_fma_f32 v121, v113, v121, v121
	v_fma_f32 v122, v114, v122, v122
	v_fma_f32 v123, v115, v123, v123
	v_fma_f32 v124, v116, v124, v124
	v_fma_f32 v125, v117, v125, v125
	v_fma_f32 v126, v118, v126, v126
	v_fma_f32 v127, v119, v127, v127
	v_mul_f32_e32 v64, v64, v120
	v_mul_f32_e32 v65, v65, v121
	v_mul_f32_e32 v66, v66, v122
	v_mul_f32_e32 v67, v67, v123
	v_mul_f32_e32 v68, v68, v124
	v_mul_f32_e32 v69, v69, v125
	v_mul_f32_e32 v70, v70, v126
	v_mul_f32_e32 v71, v71, v127
	ds_write_b128 v110, v[64:67] offset:0
	ds_write_b128 v110, v[68:71] offset:16
	v_lshlrev_b32_e32 v72, 16, v40
	v_and_b32_e32 v73, 0xffff0000, v40
	v_lshlrev_b32_e32 v128, 16, v44
	v_and_b32_e32 v129, 0xffff0000, v44
	v_lshlrev_b32_e32 v74, 16, v41
	v_and_b32_e32 v75, 0xffff0000, v41
	v_lshlrev_b32_e32 v130, 16, v45
	v_and_b32_e32 v131, 0xffff0000, v45
	v_lshlrev_b32_e32 v76, 16, v42
	v_and_b32_e32 v77, 0xffff0000, v42
	v_lshlrev_b32_e32 v132, 16, v46
	v_and_b32_e32 v133, 0xffff0000, v46
	v_lshlrev_b32_e32 v78, 16, v43
	v_and_b32_e32 v79, 0xffff0000, v43
	v_lshlrev_b32_e32 v134, 16, v47
	v_and_b32_e32 v135, 0xffff0000, v47
	v_mul_f32_e32 v112, 0xbfb8aa3b, v128
	v_mul_f32_e32 v113, 0xbfb8aa3b, v129
	v_mul_f32_e32 v114, 0xbfb8aa3b, v130
	v_mul_f32_e32 v115, 0xbfb8aa3b, v131
	v_mul_f32_e32 v116, 0xbfb8aa3b, v132
	v_mul_f32_e32 v117, 0xbfb8aa3b, v133
	v_mul_f32_e32 v118, 0xbfb8aa3b, v134
	v_mul_f32_e32 v119, 0xbfb8aa3b, v135
	v_exp_f32_e32 v112, v112
	v_exp_f32_e32 v113, v113
	v_exp_f32_e32 v114, v114
	v_exp_f32_e32 v115, v115
	v_exp_f32_e32 v116, v116
	v_exp_f32_e32 v117, v117
	v_exp_f32_e32 v118, v118
	v_exp_f32_e32 v119, v119
	s_nop 0
	v_add_f32_e32 v112, 1.0, v112
	v_add_f32_e32 v113, 1.0, v113
	v_add_f32_e32 v114, 1.0, v114
	v_add_f32_e32 v115, 1.0, v115
	v_add_f32_e32 v116, 1.0, v116
	v_add_f32_e32 v117, 1.0, v117
	v_add_f32_e32 v118, 1.0, v118
	v_add_f32_e32 v119, 1.0, v119
	v_rcp_f32_e32 v120, v112
	v_rcp_f32_e32 v121, v113
	v_rcp_f32_e32 v122, v114
	v_rcp_f32_e32 v123, v115
	v_rcp_f32_e32 v124, v116
	v_rcp_f32_e32 v125, v117
	v_rcp_f32_e32 v126, v118
	v_rcp_f32_e32 v127, v119
	s_nop 0
	v_fma_f32 v112, -v112, v120, 1.0
	v_fma_f32 v113, -v113, v121, 1.0
	v_fma_f32 v114, -v114, v122, 1.0
	v_fma_f32 v115, -v115, v123, 1.0
	v_fma_f32 v116, -v116, v124, 1.0
	v_fma_f32 v117, -v117, v125, 1.0
	v_fma_f32 v118, -v118, v126, 1.0
	v_fma_f32 v119, -v119, v127, 1.0
	v_fma_f32 v120, v112, v120, v120
	v_fma_f32 v121, v113, v121, v121
	v_fma_f32 v122, v114, v122, v122
	v_fma_f32 v123, v115, v123, v123
	v_fma_f32 v124, v116, v124, v124
	v_fma_f32 v125, v117, v125, v125
	v_fma_f32 v126, v118, v126, v126
	v_fma_f32 v127, v119, v127, v127
	v_mul_f32_e32 v72, v72, v120
	v_mul_f32_e32 v73, v73, v121
	v_mul_f32_e32 v74, v74, v122
	v_mul_f32_e32 v75, v75, v123
	v_mul_f32_e32 v76, v76, v124
	v_mul_f32_e32 v77, v77, v125
	v_mul_f32_e32 v78, v78, v126
	v_mul_f32_e32 v79, v79, v127
	ds_write_b128 v110, v[72:75] offset:16384
	ds_write_b128 v110, v[76:79] offset:16400
	v_lshlrev_b32_e32 v80, 16, v48
	v_and_b32_e32 v81, 0xffff0000, v48
	v_lshlrev_b32_e32 v128, 16, v52
	v_and_b32_e32 v129, 0xffff0000, v52
	v_lshlrev_b32_e32 v82, 16, v49
	v_and_b32_e32 v83, 0xffff0000, v49
	v_lshlrev_b32_e32 v130, 16, v53
	v_and_b32_e32 v131, 0xffff0000, v53
	v_lshlrev_b32_e32 v84, 16, v50
	v_and_b32_e32 v85, 0xffff0000, v50
	v_lshlrev_b32_e32 v132, 16, v54
	v_and_b32_e32 v133, 0xffff0000, v54
	v_lshlrev_b32_e32 v86, 16, v51
	v_and_b32_e32 v87, 0xffff0000, v51
	v_lshlrev_b32_e32 v134, 16, v55
	v_and_b32_e32 v135, 0xffff0000, v55
	v_mul_f32_e32 v112, 0xbfb8aa3b, v128
	v_mul_f32_e32 v113, 0xbfb8aa3b, v129
	v_mul_f32_e32 v114, 0xbfb8aa3b, v130
	v_mul_f32_e32 v115, 0xbfb8aa3b, v131
	v_mul_f32_e32 v116, 0xbfb8aa3b, v132
	v_mul_f32_e32 v117, 0xbfb8aa3b, v133
	v_mul_f32_e32 v118, 0xbfb8aa3b, v134
	v_mul_f32_e32 v119, 0xbfb8aa3b, v135
	v_exp_f32_e32 v112, v112
	v_exp_f32_e32 v113, v113
	v_exp_f32_e32 v114, v114
	v_exp_f32_e32 v115, v115
	v_exp_f32_e32 v116, v116
	v_exp_f32_e32 v117, v117
	v_exp_f32_e32 v118, v118
	v_exp_f32_e32 v119, v119
	s_nop 0
	v_add_f32_e32 v112, 1.0, v112
	v_add_f32_e32 v113, 1.0, v113
	v_add_f32_e32 v114, 1.0, v114
	v_add_f32_e32 v115, 1.0, v115
	v_add_f32_e32 v116, 1.0, v116
	v_add_f32_e32 v117, 1.0, v117
	v_add_f32_e32 v118, 1.0, v118
	v_add_f32_e32 v119, 1.0, v119
	v_rcp_f32_e32 v120, v112
	v_rcp_f32_e32 v121, v113
	v_rcp_f32_e32 v122, v114
	v_rcp_f32_e32 v123, v115
	v_rcp_f32_e32 v124, v116
	v_rcp_f32_e32 v125, v117
	v_rcp_f32_e32 v126, v118
	v_rcp_f32_e32 v127, v119
	s_nop 0
	v_fma_f32 v112, -v112, v120, 1.0
	v_fma_f32 v113, -v113, v121, 1.0
	v_fma_f32 v114, -v114, v122, 1.0
	v_fma_f32 v115, -v115, v123, 1.0
	v_fma_f32 v116, -v116, v124, 1.0
	v_fma_f32 v117, -v117, v125, 1.0
	v_fma_f32 v118, -v118, v126, 1.0
	v_fma_f32 v119, -v119, v127, 1.0
	v_fma_f32 v120, v112, v120, v120
	v_fma_f32 v121, v113, v121, v121
	v_fma_f32 v122, v114, v122, v122
	v_fma_f32 v123, v115, v123, v123
	v_fma_f32 v124, v116, v124, v124
	v_fma_f32 v125, v117, v125, v125
	v_fma_f32 v126, v118, v126, v126
	v_fma_f32 v127, v119, v127, v127
	v_mul_f32_e32 v80, v80, v120
	v_mul_f32_e32 v81, v81, v121
	v_mul_f32_e32 v82, v82, v122
	v_mul_f32_e32 v83, v83, v123
	v_mul_f32_e32 v84, v84, v124
	v_mul_f32_e32 v85, v85, v125
	v_mul_f32_e32 v86, v86, v126
	v_mul_f32_e32 v87, v87, v127
	ds_write_b128 v110, v[80:83] offset:32768
	ds_write_b128 v110, v[84:87] offset:32784
	v_lshlrev_b32_e32 v88, 16, v56
	v_and_b32_e32 v89, 0xffff0000, v56
	v_lshlrev_b32_e32 v128, 16, v60
	v_and_b32_e32 v129, 0xffff0000, v60
	v_lshlrev_b32_e32 v90, 16, v57
	v_and_b32_e32 v91, 0xffff0000, v57
	v_lshlrev_b32_e32 v130, 16, v61
	v_and_b32_e32 v131, 0xffff0000, v61
	v_lshlrev_b32_e32 v92, 16, v58
	v_and_b32_e32 v93, 0xffff0000, v58
	v_lshlrev_b32_e32 v132, 16, v62
	v_and_b32_e32 v133, 0xffff0000, v62
	v_lshlrev_b32_e32 v94, 16, v59
	v_and_b32_e32 v95, 0xffff0000, v59
	v_lshlrev_b32_e32 v134, 16, v63
	v_and_b32_e32 v135, 0xffff0000, v63
	v_mul_f32_e32 v112, 0xbfb8aa3b, v128
	v_mul_f32_e32 v113, 0xbfb8aa3b, v129
	v_mul_f32_e32 v114, 0xbfb8aa3b, v130
	v_mul_f32_e32 v115, 0xbfb8aa3b, v131
	v_mul_f32_e32 v116, 0xbfb8aa3b, v132
	v_mul_f32_e32 v117, 0xbfb8aa3b, v133
	v_mul_f32_e32 v118, 0xbfb8aa3b, v134
	v_mul_f32_e32 v119, 0xbfb8aa3b, v135
	v_exp_f32_e32 v112, v112
	v_exp_f32_e32 v113, v113
	v_exp_f32_e32 v114, v114
	v_exp_f32_e32 v115, v115
	v_exp_f32_e32 v116, v116
	v_exp_f32_e32 v117, v117
	v_exp_f32_e32 v118, v118
	v_exp_f32_e32 v119, v119
	s_nop 0
	v_add_f32_e32 v112, 1.0, v112
	v_add_f32_e32 v113, 1.0, v113
	v_add_f32_e32 v114, 1.0, v114
	v_add_f32_e32 v115, 1.0, v115
	v_add_f32_e32 v116, 1.0, v116
	v_add_f32_e32 v117, 1.0, v117
	v_add_f32_e32 v118, 1.0, v118
	v_add_f32_e32 v119, 1.0, v119
	v_rcp_f32_e32 v120, v112
	v_rcp_f32_e32 v121, v113
	v_rcp_f32_e32 v122, v114
	v_rcp_f32_e32 v123, v115
	v_rcp_f32_e32 v124, v116
	v_rcp_f32_e32 v125, v117
	v_rcp_f32_e32 v126, v118
	v_rcp_f32_e32 v127, v119
	s_nop 0
	v_fma_f32 v112, -v112, v120, 1.0
	v_fma_f32 v113, -v113, v121, 1.0
	v_fma_f32 v114, -v114, v122, 1.0
	v_fma_f32 v115, -v115, v123, 1.0
	v_fma_f32 v116, -v116, v124, 1.0
	v_fma_f32 v117, -v117, v125, 1.0
	v_fma_f32 v118, -v118, v126, 1.0
	v_fma_f32 v119, -v119, v127, 1.0
	v_fma_f32 v120, v112, v120, v120
	v_fma_f32 v121, v113, v121, v121
	v_fma_f32 v122, v114, v122, v122
	v_fma_f32 v123, v115, v123, v123
	v_fma_f32 v124, v116, v124, v124
	v_fma_f32 v125, v117, v125, v125
	v_fma_f32 v126, v118, v126, v126
	v_fma_f32 v127, v119, v127, v127
	v_mul_f32_e32 v88, v88, v120
	v_mul_f32_e32 v89, v89, v121
	v_mul_f32_e32 v90, v90, v122
	v_mul_f32_e32 v91, v91, v123
	v_mul_f32_e32 v92, v92, v124
	v_mul_f32_e32 v93, v93, v125
	v_mul_f32_e32 v94, v94, v126
	v_mul_f32_e32 v95, v95, v127
	v_cmp_gt_u32_e64 s[8:9], 14, v107
	s_and_saveexec_b64 s[0:1], s[8:9]
	ds_write_b128 v110, v[88:91] offset:49152
	ds_write_b128 v110, v[92:95] offset:49168
	s_mov_b64 exec, s[0:1]
	s_waitcnt lgkmcnt(0)
	s_barrier
	v_lshlrev_b32_e32 v114, 14, v106
	v_add_u32_e32 v114, v114, v105
	ds_read2st64_b32 v[32:33], v114 offset0:0 offset1:4
	ds_read2st64_b32 v[34:35], v114 offset0:8 offset1:12
	ds_read2st64_b32 v[36:37], v114 offset0:16 offset1:20
	ds_read2st64_b32 v[38:39], v114 offset0:24 offset1:28
	ds_read2st64_b32 v[40:41], v114 offset0:32 offset1:36
	ds_read2st64_b32 v[42:43], v114 offset0:40 offset1:44
	ds_read2st64_b32 v[44:45], v114 offset0:48 offset1:52
	ds_read2st64_b32 v[46:47], v114 offset0:56 offset1:60
	ds_read2st64_b32 v[48:49], v114 offset0:64 offset1:68
	ds_read2st64_b32 v[50:51], v114 offset0:72 offset1:76
	ds_read2st64_b32 v[52:53], v114 offset0:80 offset1:84
	ds_read2st64_b32 v[54:55], v114 offset0:88 offset1:92
	s_waitcnt lgkmcnt(4)
	ds_read2st64_b32 v[56:57], v114 offset0:96 offset1:100
	ds_read2st64_b32 v[58:59], v114 offset0:104 offset1:108
	ds_read2st64_b32 v[60:61], v114 offset0:112 offset1:116
	ds_read2st64_b32 v[62:63], v114 offset0:120 offset1:124
	ds_read2st64_b32 v[64:65], v114 offset0:128 offset1:132
	ds_read2st64_b32 v[66:67], v114 offset0:136 offset1:140
	ds_read2st64_b32 v[68:69], v114 offset0:144 offset1:148
	ds_read2st64_b32 v[70:71], v114 offset0:152 offset1:156
	ds_read2st64_b32 v[72:73], v114 offset0:160 offset1:164
	ds_read2st64_b32 v[74:75], v114 offset0:168 offset1:172
	ds_read2st64_b32 v[76:77], v114 offset0:176 offset1:180
	s_waitcnt lgkmcnt(0)
	v_fma_f32 v78, v0, v32, v31
	v_fma_f32 v79, v0, v33, v31
	v_fma_f32 v80, v0, v34, v31
	v_fma_f32 v81, v0, v35, v31
	v_fma_f32 v82, v0, v36, v31
	v_fma_f32 v83, v0, v37, v31
	v_fma_f32 v84, v0, v38, v31
	v_fma_f32 v85, v0, v39, v31
	v_fma_f32 v86, v0, v40, v31
	v_fma_f32 v87, v0, v41, v31
	v_fma_f32 v88, v0, v42, v31
	v_fma_f32 v89, v0, v43, v31
	v_fma_f32 v90, v0, v44, v31
	v_fma_f32 v91, v0, v45, v31
	v_fma_f32 v92, v0, v46, v31
	v_fma_f32 v93, v0, v47, v31
	v_fmac_f32_e32 v78, v1, v33
	v_fmac_f32_e32 v79, v1, v34
	v_fmac_f32_e32 v80, v1, v35
	v_fmac_f32_e32 v81, v1, v36
	v_fmac_f32_e32 v82, v1, v37
	v_fmac_f32_e32 v83, v1, v38
	v_fmac_f32_e32 v84, v1, v39
	v_fmac_f32_e32 v85, v1, v40
	v_fmac_f32_e32 v86, v1, v41
	v_fmac_f32_e32 v87, v1, v42
	v_fmac_f32_e32 v88, v1, v43
	v_fmac_f32_e32 v89, v1, v44
	v_fmac_f32_e32 v90, v1, v45
	v_fmac_f32_e32 v91, v1, v46
	v_fmac_f32_e32 v92, v1, v47
	v_fmac_f32_e32 v93, v1, v48
	v_fmac_f32_e32 v78, v2, v34
	v_fmac_f32_e32 v79, v2, v35
	v_fmac_f32_e32 v80, v2, v36
	v_fmac_f32_e32 v81, v2, v37
	v_fmac_f32_e32 v82, v2, v38
	v_fmac_f32_e32 v83, v2, v39
	v_fmac_f32_e32 v84, v2, v40
	v_fmac_f32_e32 v85, v2, v41
	v_fmac_f32_e32 v86, v2, v42
	v_fmac_f32_e32 v87, v2, v43
	v_fmac_f32_e32 v88, v2, v44
	v_fmac_f32_e32 v89, v2, v45
	v_fmac_f32_e32 v90, v2, v46
	v_fmac_f32_e32 v91, v2, v47
	v_fmac_f32_e32 v92, v2, v48
	v_fmac_f32_e32 v93, v2, v49
	v_fmac_f32_e32 v78, v3, v35
	v_fmac_f32_e32 v79, v3, v36
	v_fmac_f32_e32 v80, v3, v37
	v_fmac_f32_e32 v81, v3, v38
	v_fmac_f32_e32 v82, v3, v39
	v_fmac_f32_e32 v83, v3, v40
	v_fmac_f32_e32 v84, v3, v41
	v_fmac_f32_e32 v85, v3, v42
	v_fmac_f32_e32 v86, v3, v43
	v_fmac_f32_e32 v87, v3, v44
	v_fmac_f32_e32 v88, v3, v45
	v_fmac_f32_e32 v89, v3, v46
	v_fmac_f32_e32 v90, v3, v47
	v_fmac_f32_e32 v91, v3, v48
	v_fmac_f32_e32 v92, v3, v49
	v_fmac_f32_e32 v93, v3, v50
	v_fmac_f32_e32 v78, v4, v36
	v_fmac_f32_e32 v79, v4, v37
	v_fmac_f32_e32 v80, v4, v38
	v_fmac_f32_e32 v81, v4, v39
	v_fmac_f32_e32 v82, v4, v40
	v_fmac_f32_e32 v83, v4, v41
	v_fmac_f32_e32 v84, v4, v42
	v_fmac_f32_e32 v85, v4, v43
	v_fmac_f32_e32 v86, v4, v44
	v_fmac_f32_e32 v87, v4, v45
	v_fmac_f32_e32 v88, v4, v46
	v_fmac_f32_e32 v89, v4, v47
	v_fmac_f32_e32 v90, v4, v48
	v_fmac_f32_e32 v91, v4, v49
	v_fmac_f32_e32 v92, v4, v50
	v_fmac_f32_e32 v93, v4, v51
	v_fmac_f32_e32 v78, v5, v37
	v_fmac_f32_e32 v79, v5, v38
	v_fmac_f32_e32 v80, v5, v39
	v_fmac_f32_e32 v81, v5, v40
	v_fmac_f32_e32 v82, v5, v41
	v_fmac_f32_e32 v83, v5, v42
	v_fmac_f32_e32 v84, v5, v43
	v_fmac_f32_e32 v85, v5, v44
	v_fmac_f32_e32 v86, v5, v45
	v_fmac_f32_e32 v87, v5, v46
	v_fmac_f32_e32 v88, v5, v47
	v_fmac_f32_e32 v89, v5, v48
	v_fmac_f32_e32 v90, v5, v49
	v_fmac_f32_e32 v91, v5, v50
	v_fmac_f32_e32 v92, v5, v51
	v_fmac_f32_e32 v93, v5, v52
	v_fmac_f32_e32 v78, v6, v38
	v_fmac_f32_e32 v79, v6, v39
	v_fmac_f32_e32 v80, v6, v40
	v_fmac_f32_e32 v81, v6, v41
	v_fmac_f32_e32 v82, v6, v42
	v_fmac_f32_e32 v83, v6, v43
	v_fmac_f32_e32 v84, v6, v44
	v_fmac_f32_e32 v85, v6, v45
	v_fmac_f32_e32 v86, v6, v46
	v_fmac_f32_e32 v87, v6, v47
	v_fmac_f32_e32 v88, v6, v48
	v_fmac_f32_e32 v89, v6, v49
	v_fmac_f32_e32 v90, v6, v50
	v_fmac_f32_e32 v91, v6, v51
	v_fmac_f32_e32 v92, v6, v52
	v_fmac_f32_e32 v93, v6, v53
	v_fmac_f32_e32 v78, v7, v39
	v_fmac_f32_e32 v79, v7, v40
	v_fmac_f32_e32 v80, v7, v41
	v_fmac_f32_e32 v81, v7, v42
	v_fmac_f32_e32 v82, v7, v43
	v_fmac_f32_e32 v83, v7, v44
	v_fmac_f32_e32 v84, v7, v45
	v_fmac_f32_e32 v85, v7, v46
	v_fmac_f32_e32 v86, v7, v47
	v_fmac_f32_e32 v87, v7, v48
	v_fmac_f32_e32 v88, v7, v49
	v_fmac_f32_e32 v89, v7, v50
	v_fmac_f32_e32 v90, v7, v51
	v_fmac_f32_e32 v91, v7, v52
	v_fmac_f32_e32 v92, v7, v53
	v_fmac_f32_e32 v93, v7, v54
	v_fmac_f32_e32 v78, v8, v40
	v_fmac_f32_e32 v79, v8, v41
	v_fmac_f32_e32 v80, v8, v42
	v_fmac_f32_e32 v81, v8, v43
	v_fmac_f32_e32 v82, v8, v44
	v_fmac_f32_e32 v83, v8, v45
	v_fmac_f32_e32 v84, v8, v46
	v_fmac_f32_e32 v85, v8, v47
	v_fmac_f32_e32 v86, v8, v48
	v_fmac_f32_e32 v87, v8, v49
	v_fmac_f32_e32 v88, v8, v50
	v_fmac_f32_e32 v89, v8, v51
	v_fmac_f32_e32 v90, v8, v52
	v_fmac_f32_e32 v91, v8, v53
	v_fmac_f32_e32 v92, v8, v54
	v_fmac_f32_e32 v93, v8, v55
	v_fmac_f32_e32 v78, v9, v41
	v_fmac_f32_e32 v79, v9, v42
	v_fmac_f32_e32 v80, v9, v43
	v_fmac_f32_e32 v81, v9, v44
	v_fmac_f32_e32 v82, v9, v45
	v_fmac_f32_e32 v83, v9, v46
	v_fmac_f32_e32 v84, v9, v47
	v_fmac_f32_e32 v85, v9, v48
	v_fmac_f32_e32 v86, v9, v49
	v_fmac_f32_e32 v87, v9, v50
	v_fmac_f32_e32 v88, v9, v51
	v_fmac_f32_e32 v89, v9, v52
	v_fmac_f32_e32 v90, v9, v53
	v_fmac_f32_e32 v91, v9, v54
	v_fmac_f32_e32 v92, v9, v55
	v_fmac_f32_e32 v93, v9, v56
	v_fmac_f32_e32 v78, v10, v42
	v_fmac_f32_e32 v79, v10, v43
	v_fmac_f32_e32 v80, v10, v44
	v_fmac_f32_e32 v81, v10, v45
	v_fmac_f32_e32 v82, v10, v46
	v_fmac_f32_e32 v83, v10, v47
	v_fmac_f32_e32 v84, v10, v48
	v_fmac_f32_e32 v85, v10, v49
	v_fmac_f32_e32 v86, v10, v50
	v_fmac_f32_e32 v87, v10, v51
	v_fmac_f32_e32 v88, v10, v52
	v_fmac_f32_e32 v89, v10, v53
	v_fmac_f32_e32 v90, v10, v54
	v_fmac_f32_e32 v91, v10, v55
	v_fmac_f32_e32 v92, v10, v56
	v_fmac_f32_e32 v93, v10, v57
	v_fmac_f32_e32 v78, v11, v43
	v_fmac_f32_e32 v79, v11, v44
	v_fmac_f32_e32 v80, v11, v45
	v_fmac_f32_e32 v81, v11, v46
	v_fmac_f32_e32 v82, v11, v47
	v_fmac_f32_e32 v83, v11, v48
	v_fmac_f32_e32 v84, v11, v49
	v_fmac_f32_e32 v85, v11, v50
	v_fmac_f32_e32 v86, v11, v51
	v_fmac_f32_e32 v87, v11, v52
	v_fmac_f32_e32 v88, v11, v53
	v_fmac_f32_e32 v89, v11, v54
	v_fmac_f32_e32 v90, v11, v55
	v_fmac_f32_e32 v91, v11, v56
	v_fmac_f32_e32 v92, v11, v57
	v_fmac_f32_e32 v93, v11, v58
	v_fmac_f32_e32 v78, v12, v44
	v_fmac_f32_e32 v79, v12, v45
	v_fmac_f32_e32 v80, v12, v46
	v_fmac_f32_e32 v81, v12, v47
	v_fmac_f32_e32 v82, v12, v48
	v_fmac_f32_e32 v83, v12, v49
	v_fmac_f32_e32 v84, v12, v50
	v_fmac_f32_e32 v85, v12, v51
	v_fmac_f32_e32 v86, v12, v52
	v_fmac_f32_e32 v87, v12, v53
	v_fmac_f32_e32 v88, v12, v54
	v_fmac_f32_e32 v89, v12, v55
	v_fmac_f32_e32 v90, v12, v56
	v_fmac_f32_e32 v91, v12, v57
	v_fmac_f32_e32 v92, v12, v58
	v_fmac_f32_e32 v93, v12, v59
	v_fmac_f32_e32 v78, v13, v45
	v_fmac_f32_e32 v79, v13, v46
	v_fmac_f32_e32 v80, v13, v47
	v_fmac_f32_e32 v81, v13, v48
	v_fmac_f32_e32 v82, v13, v49
	v_fmac_f32_e32 v83, v13, v50
	v_fmac_f32_e32 v84, v13, v51
	v_fmac_f32_e32 v85, v13, v52
	v_fmac_f32_e32 v86, v13, v53
	v_fmac_f32_e32 v87, v13, v54
	v_fmac_f32_e32 v88, v13, v55
	v_fmac_f32_e32 v89, v13, v56
	v_fmac_f32_e32 v90, v13, v57
	v_fmac_f32_e32 v91, v13, v58
	v_fmac_f32_e32 v92, v13, v59
	v_fmac_f32_e32 v93, v13, v60
	v_fmac_f32_e32 v78, v14, v46
	v_fmac_f32_e32 v79, v14, v47
	v_fmac_f32_e32 v80, v14, v48
	v_fmac_f32_e32 v81, v14, v49
	v_fmac_f32_e32 v82, v14, v50
	v_fmac_f32_e32 v83, v14, v51
	v_fmac_f32_e32 v84, v14, v52
	v_fmac_f32_e32 v85, v14, v53
	v_fmac_f32_e32 v86, v14, v54
	v_fmac_f32_e32 v87, v14, v55
	v_fmac_f32_e32 v88, v14, v56
	v_fmac_f32_e32 v89, v14, v57
	v_fmac_f32_e32 v90, v14, v58
	v_fmac_f32_e32 v91, v14, v59
	v_fmac_f32_e32 v92, v14, v60
	v_fmac_f32_e32 v93, v14, v61
	v_fmac_f32_e32 v78, v15, v47
	v_fmac_f32_e32 v79, v15, v48
	v_fmac_f32_e32 v80, v15, v49
	v_fmac_f32_e32 v81, v15, v50
	v_fmac_f32_e32 v82, v15, v51
	v_fmac_f32_e32 v83, v15, v52
	v_fmac_f32_e32 v84, v15, v53
	v_fmac_f32_e32 v85, v15, v54
	v_fmac_f32_e32 v86, v15, v55
	v_fmac_f32_e32 v87, v15, v56
	v_fmac_f32_e32 v88, v15, v57
	v_fmac_f32_e32 v89, v15, v58
	v_fmac_f32_e32 v90, v15, v59
	v_fmac_f32_e32 v91, v15, v60
	v_fmac_f32_e32 v92, v15, v61
	v_fmac_f32_e32 v93, v15, v62
	v_fmac_f32_e32 v78, v16, v48
	v_fmac_f32_e32 v79, v16, v49
	v_fmac_f32_e32 v80, v16, v50
	v_fmac_f32_e32 v81, v16, v51
	v_fmac_f32_e32 v82, v16, v52
	v_fmac_f32_e32 v83, v16, v53
	v_fmac_f32_e32 v84, v16, v54
	v_fmac_f32_e32 v85, v16, v55
	v_fmac_f32_e32 v86, v16, v56
	v_fmac_f32_e32 v87, v16, v57
	v_fmac_f32_e32 v88, v16, v58
	v_fmac_f32_e32 v89, v16, v59
	v_fmac_f32_e32 v90, v16, v60
	v_fmac_f32_e32 v91, v16, v61
	v_fmac_f32_e32 v92, v16, v62
	v_fmac_f32_e32 v93, v16, v63
	v_fmac_f32_e32 v78, v17, v49
	v_fmac_f32_e32 v79, v17, v50
	v_fmac_f32_e32 v80, v17, v51
	v_fmac_f32_e32 v81, v17, v52
	v_fmac_f32_e32 v82, v17, v53
	v_fmac_f32_e32 v83, v17, v54
	v_fmac_f32_e32 v84, v17, v55
	v_fmac_f32_e32 v85, v17, v56
	v_fmac_f32_e32 v86, v17, v57
	v_fmac_f32_e32 v87, v17, v58
	v_fmac_f32_e32 v88, v17, v59
	v_fmac_f32_e32 v89, v17, v60
	v_fmac_f32_e32 v90, v17, v61
	v_fmac_f32_e32 v91, v17, v62
	v_fmac_f32_e32 v92, v17, v63
	v_fmac_f32_e32 v93, v17, v64
	v_fmac_f32_e32 v78, v18, v50
	v_fmac_f32_e32 v79, v18, v51
	v_fmac_f32_e32 v80, v18, v52
	v_fmac_f32_e32 v81, v18, v53
	v_fmac_f32_e32 v82, v18, v54
	v_fmac_f32_e32 v83, v18, v55
	v_fmac_f32_e32 v84, v18, v56
	v_fmac_f32_e32 v85, v18, v57
	v_fmac_f32_e32 v86, v18, v58
	v_fmac_f32_e32 v87, v18, v59
	v_fmac_f32_e32 v88, v18, v60
	v_fmac_f32_e32 v89, v18, v61
	v_fmac_f32_e32 v90, v18, v62
	v_fmac_f32_e32 v91, v18, v63
	v_fmac_f32_e32 v92, v18, v64
	v_fmac_f32_e32 v93, v18, v65
	v_fmac_f32_e32 v78, v19, v51
	v_fmac_f32_e32 v79, v19, v52
	v_fmac_f32_e32 v80, v19, v53
	v_fmac_f32_e32 v81, v19, v54
	v_fmac_f32_e32 v82, v19, v55
	v_fmac_f32_e32 v83, v19, v56
	v_fmac_f32_e32 v84, v19, v57
	v_fmac_f32_e32 v85, v19, v58
	v_fmac_f32_e32 v86, v19, v59
	v_fmac_f32_e32 v87, v19, v60
	v_fmac_f32_e32 v88, v19, v61
	v_fmac_f32_e32 v89, v19, v62
	v_fmac_f32_e32 v90, v19, v63
	v_fmac_f32_e32 v91, v19, v64
	v_fmac_f32_e32 v92, v19, v65
	v_fmac_f32_e32 v93, v19, v66
	v_fmac_f32_e32 v78, v20, v52
	v_fmac_f32_e32 v79, v20, v53
	v_fmac_f32_e32 v80, v20, v54
	v_fmac_f32_e32 v81, v20, v55
	v_fmac_f32_e32 v82, v20, v56
	v_fmac_f32_e32 v83, v20, v57
	v_fmac_f32_e32 v84, v20, v58
	v_fmac_f32_e32 v85, v20, v59
	v_fmac_f32_e32 v86, v20, v60
	v_fmac_f32_e32 v87, v20, v61
	v_fmac_f32_e32 v88, v20, v62
	v_fmac_f32_e32 v89, v20, v63
	v_fmac_f32_e32 v90, v20, v64
	v_fmac_f32_e32 v91, v20, v65
	v_fmac_f32_e32 v92, v20, v66
	v_fmac_f32_e32 v93, v20, v67
	v_fmac_f32_e32 v78, v21, v53
	v_fmac_f32_e32 v79, v21, v54
	v_fmac_f32_e32 v80, v21, v55
	v_fmac_f32_e32 v81, v21, v56
	v_fmac_f32_e32 v82, v21, v57
	v_fmac_f32_e32 v83, v21, v58
	v_fmac_f32_e32 v84, v21, v59
	v_fmac_f32_e32 v85, v21, v60
	v_fmac_f32_e32 v86, v21, v61
	v_fmac_f32_e32 v87, v21, v62
	v_fmac_f32_e32 v88, v21, v63
	v_fmac_f32_e32 v89, v21, v64
	v_fmac_f32_e32 v90, v21, v65
	v_fmac_f32_e32 v91, v21, v66
	v_fmac_f32_e32 v92, v21, v67
	v_fmac_f32_e32 v93, v21, v68
	v_fmac_f32_e32 v78, v22, v54
	v_fmac_f32_e32 v79, v22, v55
	v_fmac_f32_e32 v80, v22, v56
	v_fmac_f32_e32 v81, v22, v57
	v_fmac_f32_e32 v82, v22, v58
	v_fmac_f32_e32 v83, v22, v59
	v_fmac_f32_e32 v84, v22, v60
	v_fmac_f32_e32 v85, v22, v61
	v_fmac_f32_e32 v86, v22, v62
	v_fmac_f32_e32 v87, v22, v63
	v_fmac_f32_e32 v88, v22, v64
	v_fmac_f32_e32 v89, v22, v65
	v_fmac_f32_e32 v90, v22, v66
	v_fmac_f32_e32 v91, v22, v67
	v_fmac_f32_e32 v92, v22, v68
	v_fmac_f32_e32 v93, v22, v69
	v_fmac_f32_e32 v78, v23, v55
	v_fmac_f32_e32 v79, v23, v56
	v_fmac_f32_e32 v80, v23, v57
	v_fmac_f32_e32 v81, v23, v58
	v_fmac_f32_e32 v82, v23, v59
	v_fmac_f32_e32 v83, v23, v60
	v_fmac_f32_e32 v84, v23, v61
	v_fmac_f32_e32 v85, v23, v62
	v_fmac_f32_e32 v86, v23, v63
	v_fmac_f32_e32 v87, v23, v64
	v_fmac_f32_e32 v88, v23, v65
	v_fmac_f32_e32 v89, v23, v66
	v_fmac_f32_e32 v90, v23, v67
	v_fmac_f32_e32 v91, v23, v68
	v_fmac_f32_e32 v92, v23, v69
	v_fmac_f32_e32 v93, v23, v70
	v_fmac_f32_e32 v78, v24, v56
	v_fmac_f32_e32 v79, v24, v57
	v_fmac_f32_e32 v80, v24, v58
	v_fmac_f32_e32 v81, v24, v59
	v_fmac_f32_e32 v82, v24, v60
	v_fmac_f32_e32 v83, v24, v61
	v_fmac_f32_e32 v84, v24, v62
	v_fmac_f32_e32 v85, v24, v63
	v_fmac_f32_e32 v86, v24, v64
	v_fmac_f32_e32 v87, v24, v65
	v_fmac_f32_e32 v88, v24, v66
	v_fmac_f32_e32 v89, v24, v67
	v_fmac_f32_e32 v90, v24, v68
	v_fmac_f32_e32 v91, v24, v69
	v_fmac_f32_e32 v92, v24, v70
	v_fmac_f32_e32 v93, v24, v71
	v_fmac_f32_e32 v78, v25, v57
	v_fmac_f32_e32 v79, v25, v58
	v_fmac_f32_e32 v80, v25, v59
	v_fmac_f32_e32 v81, v25, v60
	v_fmac_f32_e32 v82, v25, v61
	v_fmac_f32_e32 v83, v25, v62
	v_fmac_f32_e32 v84, v25, v63
	v_fmac_f32_e32 v85, v25, v64
	v_fmac_f32_e32 v86, v25, v65
	v_fmac_f32_e32 v87, v25, v66
	v_fmac_f32_e32 v88, v25, v67
	v_fmac_f32_e32 v89, v25, v68
	v_fmac_f32_e32 v90, v25, v69
	v_fmac_f32_e32 v91, v25, v70
	v_fmac_f32_e32 v92, v25, v71
	v_fmac_f32_e32 v93, v25, v72
	v_fmac_f32_e32 v78, v26, v58
	v_fmac_f32_e32 v79, v26, v59
	v_fmac_f32_e32 v80, v26, v60
	v_fmac_f32_e32 v81, v26, v61
	v_fmac_f32_e32 v82, v26, v62
	v_fmac_f32_e32 v83, v26, v63
	v_fmac_f32_e32 v84, v26, v64
	v_fmac_f32_e32 v85, v26, v65
	v_fmac_f32_e32 v86, v26, v66
	v_fmac_f32_e32 v87, v26, v67
	v_fmac_f32_e32 v88, v26, v68
	v_fmac_f32_e32 v89, v26, v69
	v_fmac_f32_e32 v90, v26, v70
	v_fmac_f32_e32 v91, v26, v71
	v_fmac_f32_e32 v92, v26, v72
	v_fmac_f32_e32 v93, v26, v73
	v_fmac_f32_e32 v78, v27, v59
	v_fmac_f32_e32 v79, v27, v60
	v_fmac_f32_e32 v80, v27, v61
	v_fmac_f32_e32 v81, v27, v62
	v_fmac_f32_e32 v82, v27, v63
	v_fmac_f32_e32 v83, v27, v64
	v_fmac_f32_e32 v84, v27, v65
	v_fmac_f32_e32 v85, v27, v66
	v_fmac_f32_e32 v86, v27, v67
	v_fmac_f32_e32 v87, v27, v68
	v_fmac_f32_e32 v88, v27, v69
	v_fmac_f32_e32 v89, v27, v70
	v_fmac_f32_e32 v90, v27, v71
	v_fmac_f32_e32 v91, v27, v72
	v_fmac_f32_e32 v92, v27, v73
	v_fmac_f32_e32 v93, v27, v74
	v_fmac_f32_e32 v78, v28, v60
	v_fmac_f32_e32 v79, v28, v61
	v_fmac_f32_e32 v80, v28, v62
	v_fmac_f32_e32 v81, v28, v63
	v_fmac_f32_e32 v82, v28, v64
	v_fmac_f32_e32 v83, v28, v65
	v_fmac_f32_e32 v84, v28, v66
	v_fmac_f32_e32 v85, v28, v67
	v_fmac_f32_e32 v86, v28, v68
	v_fmac_f32_e32 v87, v28, v69
	v_fmac_f32_e32 v88, v28, v70
	v_fmac_f32_e32 v89, v28, v71
	v_fmac_f32_e32 v90, v28, v72
	v_fmac_f32_e32 v91, v28, v73
	v_fmac_f32_e32 v92, v28, v74
	v_fmac_f32_e32 v93, v28, v75
	v_fmac_f32_e32 v78, v29, v61
	v_fmac_f32_e32 v79, v29, v62
	v_fmac_f32_e32 v80, v29, v63
	v_fmac_f32_e32 v81, v29, v64
	v_fmac_f32_e32 v82, v29, v65
	v_fmac_f32_e32 v83, v29, v66
	v_fmac_f32_e32 v84, v29, v67
	v_fmac_f32_e32 v85, v29, v68
	v_fmac_f32_e32 v86, v29, v69
	v_fmac_f32_e32 v87, v29, v70
	v_fmac_f32_e32 v88, v29, v71
	v_fmac_f32_e32 v89, v29, v72
	v_fmac_f32_e32 v90, v29, v73
	v_fmac_f32_e32 v91, v29, v74
	v_fmac_f32_e32 v92, v29, v75
	v_fmac_f32_e32 v93, v29, v76
	v_fmac_f32_e32 v78, v30, v62
	v_fmac_f32_e32 v79, v30, v63
	v_fmac_f32_e32 v80, v30, v64
	v_fmac_f32_e32 v81, v30, v65
	v_fmac_f32_e32 v82, v30, v66
	v_fmac_f32_e32 v83, v30, v67
	v_fmac_f32_e32 v84, v30, v68
	v_fmac_f32_e32 v85, v30, v69
	v_fmac_f32_e32 v86, v30, v70
	v_fmac_f32_e32 v87, v30, v71
	v_fmac_f32_e32 v88, v30, v72
	v_fmac_f32_e32 v89, v30, v73
	v_fmac_f32_e32 v90, v30, v74
	v_fmac_f32_e32 v91, v30, v75
	v_fmac_f32_e32 v92, v30, v76
	v_fmac_f32_e32 v93, v30, v77
	v_add_u32_e32 v115, 0xf800, v114
	ds_write_b32 v115, v78 offset:0
	ds_write_b32 v115, v79 offset:1024
	ds_write_b32 v115, v80 offset:2048
	ds_write_b32 v115, v81 offset:3072
	ds_write_b32 v115, v82 offset:4096
	ds_write_b32 v115, v83 offset:5120
	ds_write_b32 v115, v84 offset:6144
	ds_write_b32 v115, v85 offset:7168
	ds_write_b32 v115, v86 offset:8192
	ds_write_b32 v115, v87 offset:9216
	ds_write_b32 v115, v88 offset:10240
	ds_write_b32 v115, v89 offset:11264
	ds_write_b32 v115, v90 offset:12288
	ds_write_b32 v115, v91 offset:13312
	ds_write_b32 v115, v92 offset:14336
	ds_write_b32 v115, v93 offset:15360
	s_waitcnt lgkmcnt(0)
	s_barrier
	v_lshrrev_b32_e32 v16, 6, v143
	v_lshlrev_b32_e32 v17, 12, v16
	v_add_u32_e32 v17, v17, v111
	v_add_u32_e32 v17, 0xf800, v17
	ds_read_b128 v[32:35], v17 offset:0
	ds_read_b128 v[36:39], v17 offset:1024
	ds_read_b128 v[40:43], v17 offset:2048
	ds_read_b128 v[44:47], v17 offset:3072
	v_xor_b32_e32 v120, 1, v200
	v_lshlrev_b32_e32 v120, 2, v120
	v_xor_b32_e32 v121, 2, v200
	v_lshlrev_b32_e32 v121, 2, v121
	v_xor_b32_e32 v122, 4, v200
	v_lshlrev_b32_e32 v122, 2, v122
	v_xor_b32_e32 v123, 8, v200
	v_lshlrev_b32_e32 v123, 2, v123
	v_xor_b32_e32 v124, 16, v200
	v_lshlrev_b32_e32 v124, 2, v124
	v_xor_b32_e32 v125, 32, v200
	v_lshlrev_b32_e32 v125, 2, v125
	s_waitcnt lgkmcnt(0)
	v_add_f32_e32 v48, v32, v33
	v_add_f32_e32 v48, v48, v34
	v_add_f32_e32 v48, v48, v35
	v_add_f32_e32 v49, v36, v37
	v_add_f32_e32 v49, v49, v38
	v_add_f32_e32 v49, v49, v39
	v_add_f32_e32 v50, v40, v41
	v_add_f32_e32 v50, v50, v42
	v_add_f32_e32 v50, v50, v43
	v_add_f32_e32 v51, v44, v45
	v_add_f32_e32 v51, v51, v46
	v_add_f32_e32 v51, v51, v47
	ds_bpermute_b32 v52, v120, v48
	ds_bpermute_b32 v53, v120, v49
	ds_bpermute_b32 v54, v120, v50
	ds_bpermute_b32 v55, v120, v51
	s_waitcnt lgkmcnt(0)
	v_add_f32_e32 v48, v48, v52
	v_add_f32_e32 v49, v49, v53
	v_add_f32_e32 v50, v50, v54
	v_add_f32_e32 v51, v51, v55
	ds_bpermute_b32 v52, v121, v48
	ds_bpermute_b32 v53, v121, v49
	ds_bpermute_b32 v54, v121, v50
	ds_bpermute_b32 v55, v121, v51
	s_waitcnt lgkmcnt(0)
	v_add_f32_e32 v48, v48, v52
	v_add_f32_e32 v49, v49, v53
	v_add_f32_e32 v50, v50, v54
	v_add_f32_e32 v51, v51, v55
	ds_bpermute_b32 v52, v122, v48
	ds_bpermute_b32 v53, v122, v49
	ds_bpermute_b32 v54, v122, v50
	ds_bpermute_b32 v55, v122, v51
	s_waitcnt lgkmcnt(0)
	v_add_f32_e32 v48, v48, v52
	v_add_f32_e32 v49, v49, v53
	v_add_f32_e32 v50, v50, v54
	v_add_f32_e32 v51, v51, v55
	ds_bpermute_b32 v52, v123, v48
	ds_bpermute_b32 v53, v123, v49
	ds_bpermute_b32 v54, v123, v50
	ds_bpermute_b32 v55, v123, v51
	s_waitcnt lgkmcnt(0)
	v_add_f32_e32 v48, v48, v52
	v_add_f32_e32 v49, v49, v53
	v_add_f32_e32 v50, v50, v54
	v_add_f32_e32 v51, v51, v55
	ds_bpermute_b32 v52, v124, v48
	ds_bpermute_b32 v53, v124, v49
	ds_bpermute_b32 v54, v124, v50
	ds_bpermute_b32 v55, v124, v51
	s_waitcnt lgkmcnt(0)
	v_add_f32_e32 v48, v48, v52
	v_add_f32_e32 v49, v49, v53
	v_add_f32_e32 v50, v50, v54
	v_add_f32_e32 v51, v51, v55
	ds_bpermute_b32 v52, v125, v48
	ds_bpermute_b32 v53, v125, v49
	ds_bpermute_b32 v54, v125, v50
	ds_bpermute_b32 v55, v125, v51
	s_waitcnt lgkmcnt(0)
	v_add_f32_e32 v48, v48, v52
	v_add_f32_e32 v49, v49, v53
	v_add_f32_e32 v50, v50, v54
	v_add_f32_e32 v51, v51, v55
	v_mul_f32_e32 v48, 0x3b800000, v48
	v_sub_f32_e32 v32, v32, v48
	v_sub_f32_e32 v33, v33, v48
	v_sub_f32_e32 v34, v34, v48
	v_sub_f32_e32 v35, v35, v48
	v_mul_f32_e32 v49, 0x3b800000, v49
	v_sub_f32_e32 v36, v36, v49
	v_sub_f32_e32 v37, v37, v49
	v_sub_f32_e32 v38, v38, v49
	v_sub_f32_e32 v39, v39, v49
	v_mul_f32_e32 v50, 0x3b800000, v50
	v_sub_f32_e32 v40, v40, v50
	v_sub_f32_e32 v41, v41, v50
	v_sub_f32_e32 v42, v42, v50
	v_sub_f32_e32 v43, v43, v50
	v_mul_f32_e32 v51, 0x3b800000, v51
	v_sub_f32_e32 v44, v44, v51
	v_sub_f32_e32 v45, v45, v51
	v_sub_f32_e32 v46, v46, v51
	v_sub_f32_e32 v47, v47, v51
	v_mul_f32_e32 v48, v32, v32
	v_fmac_f32_e32 v48, v33, v33
	v_fmac_f32_e32 v48, v34, v34
	v_fmac_f32_e32 v48, v35, v35
	v_mul_f32_e32 v49, v36, v36
	v_fmac_f32_e32 v49, v37, v37
	v_fmac_f32_e32 v49, v38, v38
	v_fmac_f32_e32 v49, v39, v39
	v_mul_f32_e32 v50, v40, v40
	v_fmac_f32_e32 v50, v41, v41
	v_fmac_f32_e32 v50, v42, v42
	v_fmac_f32_e32 v50, v43, v43
	v_mul_f32_e32 v51, v44, v44
	v_fmac_f32_e32 v51, v45, v45
	v_fmac_f32_e32 v51, v46, v46
	v_fmac_f32_e32 v51, v47, v47
	ds_bpermute_b32 v52, v120, v48
	ds_bpermute_b32 v53, v120, v49
	ds_bpermute_b32 v54, v120, v50
	ds_bpermute_b32 v55, v120, v51
	s_waitcnt lgkmcnt(0)
	v_add_f32_e32 v48, v48, v52
	v_add_f32_e32 v49, v49, v53
	v_add_f32_e32 v50, v50, v54
	v_add_f32_e32 v51, v51, v55
	ds_bpermute_b32 v52, v121, v48
	ds_bpermute_b32 v53, v121, v49
	ds_bpermute_b32 v54, v121, v50
	ds_bpermute_b32 v55, v121, v51
	s_waitcnt lgkmcnt(0)
	v_add_f32_e32 v48, v48, v52
	v_add_f32_e32 v49, v49, v53
	v_add_f32_e32 v50, v50, v54
	v_add_f32_e32 v51, v51, v55
	ds_bpermute_b32 v52, v122, v48
	ds_bpermute_b32 v53, v122, v49
	ds_bpermute_b32 v54, v122, v50
	ds_bpermute_b32 v55, v122, v51
	s_waitcnt lgkmcnt(0)
	v_add_f32_e32 v48, v48, v52
	v_add_f32_e32 v49, v49, v53
	v_add_f32_e32 v50, v50, v54
	v_add_f32_e32 v51, v51, v55
	ds_bpermute_b32 v52, v123, v48
	ds_bpermute_b32 v53, v123, v49
	ds_bpermute_b32 v54, v123, v50
	ds_bpermute_b32 v55, v123, v51
	s_waitcnt lgkmcnt(0)
	v_add_f32_e32 v48, v48, v52
	v_add_f32_e32 v49, v49, v53
	v_add_f32_e32 v50, v50, v54
	v_add_f32_e32 v51, v51, v55
	ds_bpermute_b32 v52, v124, v48
	ds_bpermute_b32 v53, v124, v49
	ds_bpermute_b32 v54, v124, v50
	ds_bpermute_b32 v55, v124, v51
	s_waitcnt lgkmcnt(0)
	v_add_f32_e32 v48, v48, v52
	v_add_f32_e32 v49, v49, v53
	v_add_f32_e32 v50, v50, v54
	v_add_f32_e32 v51, v51, v55
	ds_bpermute_b32 v52, v125, v48
	ds_bpermute_b32 v53, v125, v49
	ds_bpermute_b32 v54, v125, v50
	ds_bpermute_b32 v55, v125, v51
	s_waitcnt lgkmcnt(0)
	v_add_f32_e32 v48, v48, v52
	v_add_f32_e32 v49, v49, v53
	v_add_f32_e32 v50, v50, v54
	v_add_f32_e32 v51, v51, v55
	v_mul_f32_e32 v48, 0x3b800000, v48
	v_add_f32_e32 v48, 0x358637bd, v48
	v_mul_f32_e32 v49, 0x3b800000, v49
	v_add_f32_e32 v49, 0x358637bd, v49
	v_mul_f32_e32 v50, 0x3b800000, v50
	v_add_f32_e32 v50, 0x358637bd, v50
	v_mul_f32_e32 v51, 0x3b800000, v51
	v_add_f32_e32 v51, 0x358637bd, v51
	v_rsq_f32_e32 v48, v48
	v_rsq_f32_e32 v49, v49
	v_rsq_f32_e32 v50, v50
	v_rsq_f32_e32 v51, v51
	s_nop 0
	v_mul_f32_e32 v32, v32, v48
	v_mul_f32_e32 v33, v33, v48
	v_mul_f32_e32 v34, v34, v48
	v_mul_f32_e32 v35, v35, v48
	v_fma_f32 v32, v32, v96, v100
	v_fma_f32 v33, v33, v97, v101
	v_fma_f32 v34, v34, v98, v102
	v_fma_f32 v35, v35, v99, v103
	v_mul_f32_e32 v36, v36, v49
	v_mul_f32_e32 v37, v37, v49
	v_mul_f32_e32 v38, v38, v49
	v_mul_f32_e32 v39, v39, v49
	v_fma_f32 v36, v36, v96, v100
	v_fma_f32 v37, v37, v97, v101
	v_fma_f32 v38, v38, v98, v102
	v_fma_f32 v39, v39, v99, v103
	v_mul_f32_e32 v40, v40, v50
	v_mul_f32_e32 v41, v41, v50
	v_mul_f32_e32 v42, v42, v50
	v_mul_f32_e32 v43, v43, v50
	v_fma_f32 v40, v40, v96, v100
	v_fma_f32 v41, v41, v97, v101
	v_fma_f32 v42, v42, v98, v102
	v_fma_f32 v43, v43, v99, v103
	v_mul_f32_e32 v44, v44, v51
	v_mul_f32_e32 v45, v45, v51
	v_mul_f32_e32 v46, v46, v51
	v_mul_f32_e32 v47, v47, v51
	v_fma_f32 v44, v44, v96, v100
	v_fma_f32 v45, v45, v97, v101
	v_fma_f32 v46, v46, v98, v102
	v_fma_f32 v47, v47, v99, v103
	v_mul_f32_e32 v0, 0xbfb8aa3b, v32
	v_mul_f32_e32 v1, 0xbfb8aa3b, v33
	v_mul_f32_e32 v2, 0xbfb8aa3b, v34
	v_mul_f32_e32 v3, 0xbfb8aa3b, v35
	v_mul_f32_e32 v4, 0xbfb8aa3b, v36
	v_mul_f32_e32 v5, 0xbfb8aa3b, v37
	v_mul_f32_e32 v6, 0xbfb8aa3b, v38
	v_mul_f32_e32 v7, 0xbfb8aa3b, v39
	v_exp_f32_e32 v0, v0
	v_exp_f32_e32 v1, v1
	v_exp_f32_e32 v2, v2
	v_exp_f32_e32 v3, v3
	v_exp_f32_e32 v4, v4
	v_exp_f32_e32 v5, v5
	v_exp_f32_e32 v6, v6
	v_exp_f32_e32 v7, v7
	s_nop 0
	v_add_f32_e32 v0, 1.0, v0
	v_add_f32_e32 v1, 1.0, v1
	v_add_f32_e32 v2, 1.0, v2
	v_add_f32_e32 v3, 1.0, v3
	v_add_f32_e32 v4, 1.0, v4
	v_add_f32_e32 v5, 1.0, v5
	v_add_f32_e32 v6, 1.0, v6
	v_add_f32_e32 v7, 1.0, v7
	v_rcp_f32_e32 v8, v0
	v_rcp_f32_e32 v9, v1
	v_rcp_f32_e32 v10, v2
	v_rcp_f32_e32 v11, v3
	v_rcp_f32_e32 v12, v4
	v_rcp_f32_e32 v13, v5
	v_rcp_f32_e32 v14, v6
	v_rcp_f32_e32 v15, v7
	s_nop 0
	v_fma_f32 v0, -v0, v8, 1.0
	v_fma_f32 v1, -v1, v9, 1.0
	v_fma_f32 v2, -v2, v10, 1.0
	v_fma_f32 v3, -v3, v11, 1.0
	v_fma_f32 v4, -v4, v12, 1.0
	v_fma_f32 v5, -v5, v13, 1.0
	v_fma_f32 v6, -v6, v14, 1.0
	v_fma_f32 v7, -v7, v15, 1.0
	v_fma_f32 v8, v0, v8, v8
	v_fma_f32 v9, v1, v9, v9
	v_fma_f32 v10, v2, v10, v10
	v_fma_f32 v11, v3, v11, v11
	v_fma_f32 v12, v4, v12, v12
	v_fma_f32 v13, v5, v13, v13
	v_fma_f32 v14, v6, v14, v14
	v_fma_f32 v15, v7, v15, v15
	v_mul_f32_e32 v32, v32, v8
	v_mul_f32_e32 v33, v33, v9
	v_mul_f32_e32 v34, v34, v10
	v_mul_f32_e32 v35, v35, v11
	v_mul_f32_e32 v36, v36, v12
	v_mul_f32_e32 v37, v37, v13
	v_mul_f32_e32 v38, v38, v14
	v_mul_f32_e32 v39, v39, v15
	v_mul_f32_e32 v0, 0xbfb8aa3b, v40
	v_mul_f32_e32 v1, 0xbfb8aa3b, v41
	v_mul_f32_e32 v2, 0xbfb8aa3b, v42
	v_mul_f32_e32 v3, 0xbfb8aa3b, v43
	v_mul_f32_e32 v4, 0xbfb8aa3b, v44
	v_mul_f32_e32 v5, 0xbfb8aa3b, v45
	v_mul_f32_e32 v6, 0xbfb8aa3b, v46
	v_mul_f32_e32 v7, 0xbfb8aa3b, v47
	v_exp_f32_e32 v0, v0
	v_exp_f32_e32 v1, v1
	v_exp_f32_e32 v2, v2
	v_exp_f32_e32 v3, v3
	v_exp_f32_e32 v4, v4
	v_exp_f32_e32 v5, v5
	v_exp_f32_e32 v6, v6
	v_exp_f32_e32 v7, v7
	s_nop 0
	v_add_f32_e32 v0, 1.0, v0
	v_add_f32_e32 v1, 1.0, v1
	v_add_f32_e32 v2, 1.0, v2
	v_add_f32_e32 v3, 1.0, v3
	v_add_f32_e32 v4, 1.0, v4
	v_add_f32_e32 v5, 1.0, v5
	v_add_f32_e32 v6, 1.0, v6
	v_add_f32_e32 v7, 1.0, v7
	v_rcp_f32_e32 v8, v0
	v_rcp_f32_e32 v9, v1
	v_rcp_f32_e32 v10, v2
	v_rcp_f32_e32 v11, v3
	v_rcp_f32_e32 v12, v4
	v_rcp_f32_e32 v13, v5
	v_rcp_f32_e32 v14, v6
	v_rcp_f32_e32 v15, v7
	s_nop 0
	v_fma_f32 v0, -v0, v8, 1.0
	v_fma_f32 v1, -v1, v9, 1.0
	v_fma_f32 v2, -v2, v10, 1.0
	v_fma_f32 v3, -v3, v11, 1.0
	v_fma_f32 v4, -v4, v12, 1.0
	v_fma_f32 v5, -v5, v13, 1.0
	v_fma_f32 v6, -v6, v14, 1.0
	v_fma_f32 v7, -v7, v15, 1.0
	v_fma_f32 v8, v0, v8, v8
	v_fma_f32 v9, v1, v9, v9
	v_fma_f32 v10, v2, v10, v10
	v_fma_f32 v11, v3, v11, v11
	v_fma_f32 v12, v4, v12, v12
	v_fma_f32 v13, v5, v13, v13
	v_fma_f32 v14, v6, v14, v14
	v_fma_f32 v15, v7, v15, v15
	v_mul_f32_e32 v40, v40, v8
	v_mul_f32_e32 v41, v41, v9
	v_mul_f32_e32 v42, v42, v10
	v_mul_f32_e32 v43, v43, v11
	v_mul_f32_e32 v44, v44, v12
	v_mul_f32_e32 v45, v45, v13
	v_mul_f32_e32 v46, v46, v14
	v_mul_f32_e32 v47, v47, v15
	v_readlane_b32 s2, v244, 1
	v_readlane_b32 s3, v244, 2
	s_add_i32 s0, s71, s70
	s_lshl_b32 s0, s0, 9
	s_add_u32 s2, s2, s0
	s_addc_u32 s3, s3, 0
	v_lshlrev_b32_e32 v18, 11, v16
	v_lshrrev_b32_e32 v19, 1, v111
	v_add_u32_e32 v18, v18, v19
	v_bfe_u32 v112, v32, 16, 1
	v_bfe_u32 v113, v33, 16, 1
	v_add3_u32 v112, v32, v112, s77
	v_add3_u32 v113, v33, v113, s77
	v_lshrrev_b32_e32 v112, 16, v112
	v_and_or_b32 v58, v113, s35, v112
	v_bfe_u32 v112, v34, 16, 1
	v_bfe_u32 v113, v35, 16, 1
	v_add3_u32 v112, v34, v112, s77
	v_add3_u32 v113, v35, v113, s77
	v_lshrrev_b32_e32 v112, 16, v112
	v_and_or_b32 v59, v113, s35, v112
	global_store_dwordx2 v18, v[58:59], s[2:3] offset:0
	v_bfe_u32 v112, v36, 16, 1
	v_bfe_u32 v113, v37, 16, 1
	v_add3_u32 v112, v36, v112, s77
	v_add3_u32 v113, v37, v113, s77
	v_lshrrev_b32_e32 v112, 16, v112
	v_and_or_b32 v60, v113, s35, v112
	v_bfe_u32 v112, v38, 16, 1
	v_bfe_u32 v113, v39, 16, 1
	v_add3_u32 v112, v38, v112, s77
	v_add3_u32 v113, v39, v113, s77
	v_lshrrev_b32_e32 v112, 16, v112
	v_and_or_b32 v61, v113, s35, v112
	global_store_dwordx2 v18, v[60:61], s[2:3] offset:512
	v_bfe_u32 v112, v40, 16, 1
	v_bfe_u32 v113, v41, 16, 1
	v_add3_u32 v112, v40, v112, s77
	v_add3_u32 v113, v41, v113, s77
	v_lshrrev_b32_e32 v112, 16, v112
	v_and_or_b32 v62, v113, s35, v112
	v_bfe_u32 v112, v42, 16, 1
	v_bfe_u32 v113, v43, 16, 1
	v_add3_u32 v112, v42, v112, s77
	v_add3_u32 v113, v43, v113, s77
	v_lshrrev_b32_e32 v112, 16, v112
	v_and_or_b32 v63, v113, s35, v112
	global_store_dwordx2 v18, v[62:63], s[2:3] offset:1024
	v_bfe_u32 v112, v44, 16, 1
	v_bfe_u32 v113, v45, 16, 1
	v_add3_u32 v112, v44, v112, s77
	v_add3_u32 v113, v45, v113, s77
	v_lshrrev_b32_e32 v112, 16, v112
	v_and_or_b32 v64, v113, s35, v112
	v_bfe_u32 v112, v46, 16, 1
	v_bfe_u32 v113, v47, 16, 1
	v_add3_u32 v112, v46, v112, s77
	v_add3_u32 v113, v47, v113, s77
	v_lshrrev_b32_e32 v112, 16, v112
	v_and_or_b32 v65, v113, s35, v112
	global_store_dwordx2 v18, v[64:65], s[2:3] offset:1536
	s_barrier
	s_mov_b64 s[0:1], 0
